# previous stack + SGU staging wait vmcnt(0)->vmcnt(11) (u-value loads stay in flight)
# speedup vs baseline: 1.0094x; 1.0019x over previous
; __device__ __forceinline__ float ss2f(unsigned long long v) { return (float)v * (1.0f / 16777216.0f); }
; #define GAS __attribute__((address_space(1)))
; __device__ __forceinline__ void sgu_phase(const Params& p, int o, char* lds) {
;     ...
;     u32x2 uw[2][4];
; #pragma unroll
;     for (int nt = 0; nt < 2; ++nt)
; #pragma unroll
;       for (int mt = 0; mt < 4; ++mt) uw[nt][mt] = *(const GAS u32x2*)(big + (T0 + wr * 32 + nt * 16 + fr) * 2048 + g * 128 + wc * 64 + mt * 16 + 4 * quad);
;     __syncthreads();
; #pragma unroll
;     for (int i = 0; i < 4; ++i) { const int q = sq0 + 32 * i; const u32x4 w = vst[i];
;       unsigned short* d = (unsigned short*)(lds + OFF_VT + (sc8) * VT_PITCH + q * 2);
;       d[0 * (VT_PITCH / 2)] = (unsigned short)(w.x & 0xffffu); d[1 * (VT_PITCH / 2)] = (unsigned short)(w.x >> 16);
;       d[2 * (VT_PITCH / 2)] = (unsigned short)(w.y & 0xffffu); d[3 * (VT_PITCH / 2)] = (unsigned short)(w.y >> 16);
;       d[4 * (VT_PITCH / 2)] = (unsigned short)(w.z & 0xffffu); d[5 * (VT_PITCH / 2)] = (unsigned short)(w.z >> 16);
;       d[6 * (VT_PITCH / 2)] = (unsigned short)(w.w & 0xffffu); d[7 * (VT_PITCH / 2)] = (unsigned short)(w.w >> 16); }
;     if (tid < 128) rs[tid] = __builtin_amdgcn_rsqf(pg8::ss2f(vsn) * (1.0f / 1024.0f) + EPS);
.LBB0_34:
	s_ashr_i32 s0, s8, 3
	s_ashr_i32 s1, s0, 31
	s_lshl_b64 s[42:43], s[0:1], 7
	v_lshl_add_u64 v[94:95], s[42:43], 0, v[70:71]
	s_lshl_b32 s0, s2, 1
	s_mov_b32 s1, s3
	v_lshl_add_u64 v[96:97], v[74:75], 0, s[0:1]
	v_lshlrev_b64 v[94:95], 12, v[94:95]
	v_lshl_add_u64 v[94:95], v[96:97], 0, v[94:95]
	global_load_dwordx2 v[108:109], v[94:95], off
	global_load_dwordx2 v[106:107], v[94:95], off offset:32
	global_load_dwordx2 v[104:105], v[94:95], off offset:64
	global_load_dwordx2 v[102:103], v[94:95], off offset:96
	v_add_co_u32_e32 v94, vcc, s11, v94
	s_nop 1
	v_addc_co_u32_e32 v95, vcc, 0, v95, vcc
	global_load_dwordx2 v[100:101], v[94:95], off
	global_load_dwordx2 v[98:99], v[94:95], off offset:32
	global_load_dwordx2 v[96:97], v[94:95], off offset:64
	s_nop 0
	global_load_dwordx2 v[94:95], v[94:95], off offset:96
	s_barrier
	s_waitcnt vmcnt(11)
	ds_write_b16 v112, v0
	ds_write_b16_d16_hi v112, v0 offset:272
	ds_write_b16 v112, v1 offset:544
	ds_write_b16_d16_hi v112, v1 offset:816
	ds_write_b16 v112, v2 offset:1088
	ds_write_b16_d16_hi v112, v2 offset:1360
	ds_write_b16 v112, v3 offset:1632
	ds_write_b16_d16_hi v112, v3 offset:1904
	s_waitcnt vmcnt(10)
	ds_write_b16 v112, v4 offset:64
	ds_write_b16_d16_hi v112, v4 offset:336
	ds_write_b16 v112, v5 offset:608
	ds_write_b16_d16_hi v112, v5 offset:880
	ds_write_b16 v112, v6 offset:1152
	ds_write_b16_d16_hi v112, v6 offset:1424
	ds_write_b16 v112, v7 offset:1696
	ds_write_b16_d16_hi v112, v7 offset:1968
	s_waitcnt vmcnt(9)
	ds_write_b16 v112, v8 offset:128
	ds_write_b16_d16_hi v112, v8 offset:400
	ds_write_b16 v112, v9 offset:672
	ds_write_b16_d16_hi v112, v9 offset:944
	ds_write_b16 v112, v10 offset:1216
	ds_write_b16_d16_hi v112, v10 offset:1488
	ds_write_b16 v112, v11 offset:1760
	ds_write_b16_d16_hi v112, v11 offset:2032
	s_waitcnt vmcnt(8)
	ds_write_b16 v112, v12 offset:192
	ds_write_b16_d16_hi v112, v12 offset:464
	ds_write_b16 v112, v13 offset:736
	ds_write_b16_d16_hi v112, v13 offset:1008
	ds_write_b16 v112, v14 offset:1280
	ds_write_b16_d16_hi v112, v14 offset:1552
	ds_write_b16 v112, v15 offset:1824
	ds_write_b16_d16_hi v112, v15 offset:2096
	s_and_saveexec_b64 s[0:1], s[40:41]
	s_cbranch_execz .LBB0_36
	v_ffbh_u32_e32 v67, v69
	v_min_u32_e32 v67, 32, v67
	v_lshlrev_b64 v[114:115], v67, v[68:69]
	v_min_u32_e32 v114, 1, v114
	v_or_b32_e32 v114, v115, v114
	v_cvt_f32_u32_e32 v114, v114
	v_sub_u32_e32 v67, 32, v67
	v_ldexp_f32 v67, v114, v67
	v_mul_f32_e32 v67, 0x33800000, v67
	v_fmamk_f32 v67, v67, 0x3a800000, v233
	v_rsq_f32_e32 v67, v67
	ds_write_b32 v93, v67 offset:34816
